# GLA G3 item: de-serialised q/k, decay-input, V-tile and Up-state load ladders (one wait instead of ~74)
# speedup vs baseline: 1.0218x; 1.0218x over previous
.LBB0_153:
	s_andn2_b64 vcc, exec, s[0:1]
	s_cbranch_vccnz .LBB0_135
	v_mov_b32_e32 v7, v208
	s_ashr_i32 s24, s27, 2
	s_lshl_b32 s31, s24, 6
	v_ashrrev_i32_e32 v6, 2, v7
	v_and_b32_e32 v8, -16, v6
	v_lshrrev_b32_e32 v9, 2, v7
	v_add_u32_e32 v2, s31, v8
	v_and_b32_e32 v10, 12, v9
	v_or_b32_e32 v56, v2, v10
	v_mov_b64_e32 v[0:1], s[70:71]
	s_and_b32 s30, s27, 3
	v_mad_i64_i32 v[4:5], s[0:1], v56, s56, v[0:1]
	v_and_b32_e32 v54, 15, v7
	s_lshl_b32 s0, s30, 8
	s_mov_b32 s1, s29
	v_lshl_add_u64 v[4:5], v[4:5], 0, s[0:1]
	v_lshlrev_b32_e32 v58, 1, v54
	v_mov_b32_e32 v59, v129
	v_lshl_add_u64 v[4:5], v[4:5], 0, v[58:59]
	v_or_b32_e32 v52, 1, v56
	global_load_ushort v108, v[4:5], off offset:2048
	global_load_ushort v107, v[4:5], off offset:2080
	global_load_ushort v106, v[4:5], off offset:2112
	global_load_ushort v105, v[4:5], off offset:2144
	global_load_ushort v104, v[4:5], off offset:2176
	global_load_ushort v103, v[4:5], off offset:2208
	global_load_ushort v102, v[4:5], off offset:2240
	global_load_ushort v101, v[4:5], off offset:2272
	v_mad_i64_i32 v[4:5], s[36:37], v52, s56, v[0:1]
	v_lshl_add_u64 v[4:5], v[4:5], 0, s[0:1]
	v_lshl_add_u64 v[4:5], v[4:5], 0, v[58:59]
	v_or_b32_e32 v50, 2, v56
	global_load_ushort v100, v[4:5], off offset:2048
	global_load_ushort v99, v[4:5], off offset:2080
	global_load_ushort v98, v[4:5], off offset:2112
	global_load_ushort v97, v[4:5], off offset:2144
	global_load_ushort v96, v[4:5], off offset:2176
	global_load_ushort v95, v[4:5], off offset:2208
	global_load_ushort v94, v[4:5], off offset:2240
	global_load_ushort v93, v[4:5], off offset:2272
	v_mad_i64_i32 v[4:5], s[36:37], v50, s56, v[0:1]
	v_lshl_add_u64 v[4:5], v[4:5], 0, s[0:1]
	v_lshl_add_u64 v[4:5], v[4:5], 0, v[58:59]
	v_or_b32_e32 v48, 3, v56
	global_load_ushort v92, v[4:5], off offset:2048
	global_load_ushort v91, v[4:5], off offset:2080
	global_load_ushort v90, v[4:5], off offset:2112
	global_load_ushort v89, v[4:5], off offset:2144
	global_load_ushort v88, v[4:5], off offset:2176
	global_load_ushort v87, v[4:5], off offset:2208
	global_load_ushort v86, v[4:5], off offset:2240
	global_load_ushort v85, v[4:5], off offset:2272
	v_mad_i64_i32 v[4:5], s[36:37], v48, s56, v[0:1]
	v_lshl_add_u64 v[4:5], v[4:5], 0, s[0:1]
	v_lshl_add_u64 v[4:5], v[4:5], 0, v[58:59]
	s_lshl_b32 s28, s30, 7
	global_load_ushort v79, v[4:5], off offset:2048
	global_load_ushort v78, v[4:5], off offset:2080
	global_load_ushort v59, v[4:5], off offset:2112
	global_load_ushort v57, v[4:5], off offset:2144
	global_load_ushort v55, v[4:5], off offset:2176
	global_load_ushort v53, v[4:5], off offset:2208
	global_load_ushort v51, v[4:5], off offset:2240
	global_load_ushort v49, v[4:5], off offset:2272
	v_and_b32_e32 v11, 63, v7
	v_mad_i64_i32 v[4:5], s[36:37], v2, s56, v[0:1]
	v_lshl_add_u64 v[4:5], v[4:5], 0, s[28:29]
	v_lshlrev_b32_e32 v128, 1, v11
	v_lshl_add_u64 v[4:5], v[4:5], 0, v[128:129]
	global_load_ushort v109, v[4:5], off
	s_lshl_b32 s26, s30, 6
	v_readlane_b32 s25, v255, 48
	s_movk_i32 s38, 0x2000
	s_movk_i32 s39, 0x3000
	v_readlane_b32 s40, v252, 39
	v_readlane_b32 s54, v252, 53
	v_readlane_b32 s55, v252, 54
	v_readlane_b32 s41, v252, 40
	v_readlane_b32 s52, v252, 51
	v_readlane_b32 s53, v252, 52
	v_readlane_b32 s42, v252, 41
	v_readlane_b32 s43, v252, 42
	v_readlane_b32 s44, v252, 43
	v_readlane_b32 s45, v252, 44
	v_readlane_b32 s46, v252, 45
	v_readlane_b32 s47, v252, 46
	v_readlane_b32 s48, v252, 47
	v_readlane_b32 s49, v252, 48
	v_readlane_b32 s50, v252, 49
	v_readlane_b32 s51, v252, 50
	v_mul_u32_u24_e32 v19, 0x90, v54
	v_mov_b32_e32 v28, 0
	v_mov_b32_e32 v29, v28
	v_mov_b32_e32 v30, v28
	v_mov_b32_e32 v31, v28
	v_mov_b32_e32 v24, v28
	v_mov_b32_e32 v25, v28
	v_mov_b32_e32 v26, v28
	v_mov_b32_e32 v27, v28
	v_mov_b32_e32 v23, v28
	global_load_ushort v110, v[4:5], off offset:512
	v_or_b32_e32 v3, 1, v2
	v_mad_i64_i32 v[4:5], s[36:37], v3, s56, v[0:1]
	v_lshl_add_u64 v[4:5], v[4:5], 0, s[28:29]
	v_lshl_add_u64 v[4:5], v[4:5], 0, v[128:129]
	global_load_ushort v111, v[4:5], off
	global_load_ushort v112, v[4:5], off offset:512
	v_or_b32_e32 v3, 2, v2
	v_mad_i64_i32 v[4:5], s[36:37], v3, s56, v[0:1]
	v_lshl_add_u64 v[4:5], v[4:5], 0, s[28:29]
	v_lshl_add_u64 v[4:5], v[4:5], 0, v[128:129]
	global_load_ushort v113, v[4:5], off
	global_load_ushort v114, v[4:5], off offset:512
	v_or_b32_e32 v3, 3, v2
	v_mad_i64_i32 v[4:5], s[36:37], v3, s56, v[0:1]
	v_lshl_add_u64 v[4:5], v[4:5], 0, s[28:29]
	v_lshl_add_u64 v[4:5], v[4:5], 0, v[128:129]
	global_load_ushort v115, v[4:5], off
	global_load_ushort v116, v[4:5], off offset:512
	v_or_b32_e32 v3, 4, v2
	v_mad_i64_i32 v[4:5], s[36:37], v3, s56, v[0:1]
	v_lshl_add_u64 v[4:5], v[4:5], 0, s[28:29]
	v_lshl_add_u64 v[4:5], v[4:5], 0, v[128:129]
	global_load_ushort v117, v[4:5], off
	global_load_ushort v118, v[4:5], off offset:512
	v_or_b32_e32 v3, 5, v2
	v_mad_i64_i32 v[4:5], s[36:37], v3, s56, v[0:1]
	v_lshl_add_u64 v[4:5], v[4:5], 0, s[28:29]
	v_lshl_add_u64 v[4:5], v[4:5], 0, v[128:129]
	global_load_ushort v119, v[4:5], off
	global_load_ushort v120, v[4:5], off offset:512
	v_or_b32_e32 v3, 6, v2
	v_mad_i64_i32 v[4:5], s[36:37], v3, s56, v[0:1]
	v_lshl_add_u64 v[4:5], v[4:5], 0, s[28:29]
	v_lshl_add_u64 v[4:5], v[4:5], 0, v[128:129]
	global_load_ushort v121, v[4:5], off
	global_load_ushort v122, v[4:5], off offset:512
	v_or_b32_e32 v3, 7, v2
	v_mad_i64_i32 v[4:5], s[36:37], v3, s56, v[0:1]
	v_lshl_add_u64 v[4:5], v[4:5], 0, s[28:29]
	v_lshl_add_u64 v[4:5], v[4:5], 0, v[128:129]
	global_load_ushort v123, v[4:5], off
	global_load_ushort v124, v[4:5], off offset:512
	v_or_b32_e32 v3, 8, v2
	v_mad_i64_i32 v[4:5], s[36:37], v3, s56, v[0:1]
	v_lshl_add_u64 v[4:5], v[4:5], 0, s[28:29]
	v_lshl_add_u64 v[4:5], v[4:5], 0, v[128:129]
	global_load_ushort v125, v[4:5], off
	global_load_ushort v126, v[4:5], off offset:512
	v_or_b32_e32 v3, 9, v2
	v_mad_i64_i32 v[4:5], s[36:37], v3, s56, v[0:1]
	v_lshl_add_u64 v[4:5], v[4:5], 0, s[28:29]
	v_lshl_add_u64 v[4:5], v[4:5], 0, v[128:129]
	global_load_ushort v127, v[4:5], off
	global_load_ushort v133, v[4:5], off offset:512
	v_or_b32_e32 v3, 10, v2
	v_mad_i64_i32 v[4:5], s[36:37], v3, s56, v[0:1]
	v_lshl_add_u64 v[4:5], v[4:5], 0, s[28:29]
	v_lshl_add_u64 v[4:5], v[4:5], 0, v[128:129]
	global_load_ushort v134, v[4:5], off
	global_load_ushort v135, v[4:5], off offset:512
	v_or_b32_e32 v3, 11, v2
	v_mad_i64_i32 v[4:5], s[36:37], v3, s56, v[0:1]
	v_lshl_add_u64 v[4:5], v[4:5], 0, s[28:29]
	v_lshl_add_u64 v[4:5], v[4:5], 0, v[128:129]
	global_load_ushort v136, v[4:5], off
	global_load_ushort v137, v[4:5], off offset:512
	v_or_b32_e32 v3, 12, v2
	v_mad_i64_i32 v[4:5], s[36:37], v3, s56, v[0:1]
	v_lshl_add_u64 v[4:5], v[4:5], 0, s[28:29]
	v_lshl_add_u64 v[4:5], v[4:5], 0, v[128:129]
	global_load_ushort v138, v[4:5], off
	global_load_ushort v139, v[4:5], off offset:512
	v_or_b32_e32 v3, 13, v2
	v_mad_i64_i32 v[4:5], s[36:37], v3, s56, v[0:1]
	v_lshl_add_u64 v[4:5], v[4:5], 0, s[28:29]
	v_lshl_add_u64 v[4:5], v[4:5], 0, v[128:129]
	global_load_ushort v140, v[4:5], off
	global_load_ushort v141, v[4:5], off offset:512
	v_or_b32_e32 v3, 14, v2
	v_mad_i64_i32 v[4:5], s[36:37], v3, s56, v[0:1]
	v_lshl_add_u64 v[4:5], v[4:5], 0, s[28:29]
	v_lshl_add_u64 v[4:5], v[4:5], 0, v[128:129]
	global_load_ushort v142, v[4:5], off
	v_or_b32_e32 v2, 15, v2
	global_load_ushort v143, v[4:5], off offset:512
	v_mad_i64_i32 v[2:3], s[36:37], v2, s56, v[0:1]
	v_lshl_add_u64 v[2:3], v[2:3], 0, s[28:29]
	v_lshl_add_u64 v[2:3], v[2:3], 0, v[128:129]
	global_load_ushort v4, v[2:3], off
	s_add_u32 s36, s25, s0
	global_load_ushort v2, v[2:3], off offset:512
	v_readlane_b32 s25, v255, 49
	s_addc_u32 s37, s25, 0
	v_mov_b32_e32 v3, v129
	s_mov_b32 s25, 0
	s_waitcnt vmcnt(0)
	v_lshlrev_b32_e32 v109, 16, v109
	v_mul_f32_e32 v109, 0x3e000000, v109
	v_lshlrev_b32_e32 v110, 16, v110
	v_lshlrev_b32_e32 v111, 16, v111
	v_mul_f32_e32 v111, 0x3e000000, v111
	v_lshlrev_b32_e32 v112, 16, v112
	v_lshlrev_b32_e32 v113, 16, v113
	v_mul_f32_e32 v113, 0x3e000000, v113
	v_lshlrev_b32_e32 v114, 16, v114
	v_lshlrev_b32_e32 v115, 16, v115
	v_mul_f32_e32 v115, 0x3e000000, v115
	v_lshlrev_b32_e32 v116, 16, v116
	v_lshlrev_b32_e32 v117, 16, v117
	v_mul_f32_e32 v117, 0x3e000000, v117
	v_lshlrev_b32_e32 v118, 16, v118
	v_lshlrev_b32_e32 v119, 16, v119
	v_mul_f32_e32 v119, 0x3e000000, v119
	v_lshlrev_b32_e32 v120, 16, v120
	v_lshlrev_b32_e32 v121, 16, v121
	v_mul_f32_e32 v121, 0x3e000000, v121
	v_lshlrev_b32_e32 v122, 16, v122
	v_lshlrev_b32_e32 v123, 16, v123
	v_mul_f32_e32 v123, 0x3e000000, v123
	v_lshlrev_b32_e32 v124, 16, v124
	v_lshlrev_b32_e32 v125, 16, v125
	v_mul_f32_e32 v125, 0x3e000000, v125
	v_lshlrev_b32_e32 v126, 16, v126
	v_lshlrev_b32_e32 v127, 16, v127
	v_mul_f32_e32 v127, 0x3e000000, v127
	v_lshlrev_b32_e32 v133, 16, v133
	v_lshlrev_b32_e32 v134, 16, v134
	v_mul_f32_e32 v134, 0x3e000000, v134
	v_lshlrev_b32_e32 v135, 16, v135
	v_lshlrev_b32_e32 v136, 16, v136
	v_mul_f32_e32 v136, 0x3e000000, v136
	v_lshlrev_b32_e32 v137, 16, v137
	v_lshlrev_b32_e32 v138, 16, v138
	v_mul_f32_e32 v138, 0x3e000000, v138
	v_lshlrev_b32_e32 v139, 16, v139
	v_lshlrev_b32_e32 v140, 16, v140
	v_mul_f32_e32 v140, 0x3e000000, v140
	v_lshlrev_b32_e32 v141, 16, v141
	v_lshlrev_b32_e32 v142, 16, v142
	v_mul_f32_e32 v142, 0x3e000000, v142
	v_lshlrev_b32_e32 v143, 16, v143
	v_lshlrev_b32_e32 v4, 16, v4
	v_mul_f32_e32 v144, 0x3e000000, v4
	v_lshlrev_b32_e32 v145, 16, v2
	v_mov_b32_e32 v2, v208
	s_nop 0
	v_and_b32_e32 v14, 63, v2
	v_lshlrev_b32_e32 v2, 2, v14
	v_lshl_add_u64 v[4:5], s[36:37], 0, v[2:3]
	global_load_dword v146, v2, s[36:37]
	global_load_dword v147, v2, s[36:37] offset:1024
	global_load_dword v148, v2, s[36:37] offset:2048
	global_load_dword v149, v2, s[36:37] offset:3072
	v_add_co_u32_e32 v2, vcc, s85, v4
	v_readlane_b32 s36, v255, 44
	s_nop 0
	v_addc_co_u32_e32 v3, vcc, 0, v5, vcc
	v_add_co_u32_e32 v12, vcc, s38, v4
	s_or_b32 s36, s26, s36
	s_nop 0
	v_addc_co_u32_e32 v13, vcc, 0, v5, vcc
	global_load_dword v150, v[12:13], off offset:-4096
	global_load_dword v151, v[2:3], off offset:1024
	global_load_dword v152, v[2:3], off offset:2048
	global_load_dword v153, v[2:3], off offset:3072
	global_load_dword v154, v[12:13], off
	global_load_dword v155, v[12:13], off offset:1024
	global_load_dword v156, v[12:13], off offset:2048
	global_load_dword v157, v[12:13], off offset:3072
	v_add_co_u32_e32 v2, vcc, s39, v4
	v_readlane_b32 s37, v255, 51
	s_nop 0
	v_addc_co_u32_e32 v3, vcc, 0, v5, vcc
	global_load_dword v158, v[2:3], off
	global_load_dword v159, v[2:3], off offset:1024
	global_load_dword v160, v[2:3], off offset:2048
	global_load_dword v161, v[2:3], off offset:3072
	v_or_b32_e32 v2, s36, v14
	v_ashrrev_i32_e32 v3, 31, v2
	v_lshl_add_u64 v[2:3], v[2:3], 2, s[54:55]
	global_load_dword v162, v[2:3], off
	v_mov_b32_e32 v2, v208
	v_readlane_b32 s36, v255, 50
	s_add_u32 s36, s36, s0
	v_and_b32_e32 v14, 63, v2
	s_addc_u32 s37, s37, 0
	v_lshlrev_b32_e32 v2, 2, v14
	v_mov_b32_e32 v3, v129
	v_lshl_add_u64 v[4:5], s[36:37], 0, v[2:3]
	global_load_dword v163, v2, s[36:37]
	global_load_dword v164, v2, s[36:37] offset:1024
	global_load_dword v165, v2, s[36:37] offset:2048
	global_load_dword v166, v2, s[36:37] offset:3072
	v_add_co_u32_e32 v2, vcc, s85, v4
	v_readlane_b32 s36, v255, 45
	s_nop 0
	v_addc_co_u32_e32 v3, vcc, 0, v5, vcc
	v_add_co_u32_e32 v12, vcc, s38, v4
	s_or_b32 s26, s26, s36
	s_nop 0
	v_addc_co_u32_e32 v13, vcc, 0, v5, vcc
	global_load_dword v167, v[12:13], off offset:-4096
	global_load_dword v168, v[2:3], off offset:1024
	global_load_dword v169, v[2:3], off offset:2048
	global_load_dword v170, v[2:3], off offset:3072
	global_load_dword v171, v[12:13], off
	global_load_dword v172, v[12:13], off offset:1024
	global_load_dword v173, v[12:13], off offset:2048
	global_load_dword v174, v[12:13], off offset:3072
	v_add_co_u32_e32 v2, vcc, s39, v4
	v_mov_b32_e32 v13, v208
	s_nop 0
	v_addc_co_u32_e32 v3, vcc, 0, v5, vcc
	global_load_dword v175, v[2:3], off
	global_load_dword v176, v[2:3], off offset:1024
	global_load_dword v177, v[2:3], off offset:2048
	global_load_dword v178, v[2:3], off offset:3072
	v_or_b32_e32 v2, s26, v14
	v_ashrrev_i32_e32 v3, 31, v2
	v_lshl_add_u64 v[2:3], v[2:3], 2, s[54:55]
	global_load_dword v179, v[2:3], off
	v_mov_b32_e32 v5, v129
	v_ashrrev_i32_e32 v2, 5, v13
	v_and_b32_e32 v4, 31, v13
	v_add_u32_e32 v2, s31, v2
	v_mad_i64_i32 v[2:3], s[36:37], v2, s56, v[0:1]
	v_lshlrev_b32_e32 v4, 1, v4
	v_lshl_add_u64 v[2:3], v[2:3], 0, v[4:5]
	global_load_ushort v232, v[2:3], off offset:3072
	v_add_u32_e32 v16, 0x100, v13
	v_lshlrev_b32_e32 v14, 2, v13
	v_mov_b32_e32 v84, v14
	v_add_u32_e32 v17, 0x200, v13
	v_add_u32_e32 v18, 0x300, v13
	s_movk_i32 s26, 0x110
	v_ashrrev_i32_e32 v2, 5, v16
	v_add_u32_e32 v2, s31, v2
	v_mad_i64_i32 v[2:3], s[36:37], v2, s56, v[0:1]
	v_lshl_add_u64 v[2:3], v[2:3], 0, v[4:5]
	global_load_ushort v233, v[2:3], off offset:3072
	v_ashrrev_i32_e32 v2, 5, v17
	v_add_u32_e32 v2, s31, v2
	v_mad_i64_i32 v[2:3], s[36:37], v2, s56, v[0:1]
	v_lshl_add_u64 v[2:3], v[2:3], 0, v[4:5]
	global_load_ushort v234, v[2:3], off offset:3072
	v_ashrrev_i32_e32 v2, 5, v18
	v_add_u32_e32 v2, s31, v2
	v_mad_i64_i32 v[2:3], s[36:37], v2, s56, v[0:1]
	v_lshl_add_u64 v[2:3], v[2:3], 0, v[4:5]
	global_load_ushort v235, v[2:3], off offset:3072
	v_add_u32_e32 v2, 0x400, v13
	v_ashrrev_i32_e32 v2, 5, v2
	v_add_u32_e32 v2, s31, v2
	v_mad_i64_i32 v[2:3], s[36:37], v2, s56, v[0:1]
	v_lshl_add_u64 v[2:3], v[2:3], 0, v[4:5]
	global_load_ushort v236, v[2:3], off offset:3072
	v_add_u32_e32 v2, 0x500, v13
	v_ashrrev_i32_e32 v2, 5, v2
	v_add_u32_e32 v2, s31, v2
	v_mad_i64_i32 v[2:3], s[36:37], v2, s56, v[0:1]
	v_lshl_add_u64 v[2:3], v[2:3], 0, v[4:5]
	global_load_ushort v237, v[2:3], off offset:3072
	v_add_u32_e32 v2, 0x600, v13
	v_ashrrev_i32_e32 v2, 5, v2
	v_add_u32_e32 v2, s31, v2
	v_mad_i64_i32 v[2:3], s[36:37], v2, s56, v[0:1]
	v_lshl_add_u64 v[2:3], v[2:3], 0, v[4:5]
	global_load_ushort v238, v[2:3], off offset:3072
	v_add_u32_e32 v2, 0x700, v13
	v_ashrrev_i32_e32 v2, 5, v2
	v_add_u32_e32 v2, s31, v2
	v_mad_i64_i32 v[2:3], s[36:37], v2, s56, v[0:1]
	v_lshl_add_u64 v[2:3], v[2:3], 0, v[4:5]
	global_load_ushort v239, v[2:3], off offset:3072
	v_ashrrev_i32_e32 v4, 4, v13
	v_lshlrev_b32_e32 v2, 4, v13
	v_and_b32_e32 v12, 0xf0, v2
	v_add_u32_e32 v2, s31, v4
	v_mad_i64_i32 v[2:3], s[36:37], v2, s56, v[0:1]
	v_lshl_add_u64 v[2:3], v[2:3], 0, s[0:1]
	v_mov_b32_e32 v13, v129
	v_lshl_add_u64 v[2:3], v[2:3], 0, v[12:13]
	v_mad_u64_u32 v[14:15], s[36:37], v4, s26, v[12:13]
	v_mov_b32_e32 v248, v14
	global_load_dwordx4 v[240:243], v[2:3], off offset:1024
	v_ashrrev_i32_e32 v4, 4, v16
	v_add_u32_e32 v2, s31, v4
	v_mad_i64_i32 v[2:3], s[36:37], v2, s56, v[0:1]
	v_lshl_add_u64 v[2:3], v[2:3], 0, s[0:1]
	v_lshl_add_u64 v[2:3], v[2:3], 0, v[12:13]
	v_mad_u64_u32 v[14:15], s[36:37], v4, s26, v[12:13]
	v_mov_b32_e32 v249, v14
	global_load_dwordx4 v[244:247], v[2:3], off offset:1024
	v_ashrrev_i32_e32 v4, 4, v17
	v_add_u32_e32 v2, s31, v4
	v_mad_i64_i32 v[2:3], s[36:37], v2, s56, v[0:1]
	v_lshl_add_u64 v[2:3], v[2:3], 0, s[0:1]
	v_lshl_add_u64 v[2:3], v[2:3], 0, v[12:13]
	v_mad_u64_u32 v[14:15], s[36:37], v4, s26, v[12:13]
	v_mov_b32_e32 v220, v14
	global_load_dwordx4 v[216:219], v[2:3], off offset:1024
	v_mul_lo_u32 v15, v8, s33
	v_ashrrev_i32_e32 v2, 4, v18
	v_add_u32_e32 v3, s31, v2
	v_mad_i64_i32 v[0:1], s[36:37], v3, s56, v[0:1]
	v_lshl_add_u64 v[0:1], v[0:1], 0, s[0:1]
	v_lshl_add_u64 v[0:1], v[0:1], 0, v[12:13]
	v_mad_u64_u32 v[4:5], s[0:1], v2, s26, v[12:13]
	global_load_dwordx4 v[80:83], v[0:1], off offset:1024
	s_movk_i32 s26, 0x90
	s_lshl_b32 s0, s24, 3
	s_lshl_b32 s1, s30, 1
	v_mul_lo_u32 v16, v8, s26
	v_or_b32_e32 v12, 48, v54
	s_or_b32 s24, s1, s0
	v_readlane_b32 s0, v253, 25
	v_lshlrev_b32_e32 v22, 1, v12
	v_readlane_b32 s1, v253, 26
	s_mov_b64 s[30:31], -1
	s_waitcnt vmcnt(0)
	v_lshlrev_b32_e32 v232, 16, v232
	v_lshlrev_b32_e32 v233, 16, v233
	ds_write2st64_b32 v84, v232, v233 offset0:69 offset1:73
	v_lshlrev_b32_e32 v234, 16, v234
	v_lshlrev_b32_e32 v235, 16, v235
	ds_write2st64_b32 v84, v234, v235 offset0:77 offset1:81
	v_lshlrev_b32_e32 v236, 16, v236
	v_lshlrev_b32_e32 v237, 16, v237
	ds_write2st64_b32 v84, v236, v237 offset0:85 offset1:89
	v_lshlrev_b32_e32 v238, 16, v238
	v_lshlrev_b32_e32 v239, 16, v239
	ds_write2st64_b32 v84, v238, v239 offset0:93 offset1:97
	ds_write_b128 v248, v[240:243] offset:44288
	ds_write_b128 v249, v[244:247] offset:44288
	ds_write_b128 v220, v[216:219] offset:44288
	ds_write_b128 v4, v[80:83] offset:44288
	v_lshrrev_b32_e32 v2, 1, v7
	v_and_b32_e32 v13, 24, v2
	v_bfi_b32 v0, -16, v6, v7
	v_and_or_b32 v2, v9, 3, v13
	v_mul_lo_u32 v5, v0, s26
	v_or_b32_e32 v0, v8, v10
	v_lshlrev_b32_e32 v4, 3, v7
	v_mul_u32_u24_e32 v9, 0x110, v2
	v_or_b32_e32 v2, 15, v6
	v_or_b32_e32 v8, 16, v54
	v_or_b32_e32 v10, 32, v54
	v_lshlrev_b32_e32 v1, 2, v11
	v_and_b32_e32 v11, 48, v7
	v_and_b32_e32 v7, 24, v4
	v_mul_lo_u32 v17, v2, s33
	v_mul_lo_u32 v18, v2, s26
	v_cmp_ge_i32_e64 s[36:37], v54, v0
	v_cmp_le_i32_e64 s[38:39], v54, v0
	v_mul_lo_u32 v180, v0, s26
	v_or_b32_e32 v2, 1, v0
	v_cmp_gt_i32_e64 s[40:41], v54, v0
	v_or_b32_e32 v4, 2, v0
	v_or_b32_e32 v6, 3, v0
	v_cmp_ge_i32_e64 s[52:53], v8, v0
	v_cmp_le_i32_e64 s[54:55], v8, v0
	v_cmp_gt_i32_e64 s[56:57], v8, v0
	v_cmp_ge_i32_e64 s[68:69], v10, v0
	v_cmp_le_i32_e64 s[70:71], v10, v0
	v_cmp_gt_i32_e64 s[72:73], v10, v0
	v_cmp_ge_i32_e64 s[84:85], v12, v0
	v_cmp_le_i32_e64 s[86:87], v12, v0
	v_cmp_gt_i32_e64 s[88:89], v12, v0
	v_lshlrev_b32_e32 v0, 6, v54
	v_sub_u32_e32 v3, v1, v128
	v_cmp_le_i32_e64 s[42:43], v54, v2
	v_cmp_ge_i32_e64 s[44:45], v54, v4
	v_cmp_le_i32_e64 s[46:47], v54, v4
	v_cmp_ge_i32_e64 s[48:49], v54, v6
	v_cmp_le_i32_e64 s[50:51], v54, v6
	v_lshlrev_b32_e32 v20, 1, v8
	v_cmp_le_i32_e64 s[58:59], v8, v2
	v_cmp_ge_i32_e64 s[60:61], v8, v4
	v_cmp_le_i32_e64 s[62:63], v8, v4
	v_cmp_ge_i32_e64 s[64:65], v8, v6
	v_cmp_le_i32_e64 s[66:67], v8, v6
	v_lshlrev_b32_e32 v21, 1, v10
	v_cmp_le_i32_e64 s[74:75], v10, v2
	v_cmp_ge_i32_e64 s[76:77], v10, v4
	v_cmp_le_i32_e64 s[78:79], v10, v4
	v_cmp_ge_i32_e64 s[80:81], v10, v6
	v_cmp_le_i32_e64 s[82:83], v10, v6
	v_cmp_le_i32_e64 s[90:91], v12, v2
	v_cmp_ge_i32_e64 s[92:93], v12, v4
	v_cmp_le_i32_e64 s[94:95], v12, v4
	v_cmp_ge_i32_e64 s[96:97], v12, v6
	v_cmp_le_i32_e64 s[98:99], v12, v6
	v_lshlrev_b32_e32 v2, 6, v8
	v_lshlrev_b32_e32 v4, 6, v10
	v_lshlrev_b32_e32 v6, 6, v12
	v_or_b32_e32 v8, 0x1000, v0
	v_or_b32_e32 v10, 0x1400, v0
	v_or_b32_e32 v12, 0x1800, v0
	v_or_b32_e32 v14, 0x1c00, v0
	v_lshlrev_b32_e32 v128, 1, v13
	v_lshl_add_u64 v[60:61], s[0:1], 0, v[128:129]
	v_add_u32_e32 v181, v1, v15
	v_add_u32_e32 v182, v3, v16
	v_add_u32_e32 v183, v1, v17
	v_add_u32_e32 v184, v3, v18
	v_add_u32_e32 v185, v5, v11
	v_add_u32_e32 v186, v11, v19
	v_add_u32_e32 v187, v20, v180
	v_add_u32_e32 v188, v21, v180
	v_add_u32_e32 v189, v22, v180
	v_add_u32_e32 v190, v7, v9
	v_lshlrev_b32_e32 v128, 1, v0
	v_lshlrev_b32_e32 v62, 1, v2
	v_lshlrev_b32_e32 v64, 1, v4
	v_lshlrev_b32_e32 v66, 1, v6
	v_lshlrev_b32_e32 v68, 1, v8
	v_lshlrev_b32_e32 v70, 1, v10
	v_lshlrev_b32_e32 v72, 1, v12
	v_lshlrev_b32_e32 v74, 1, v14
	v_mov_b32_e32 v16, v28
	v_mov_b32_e32 v17, v28
	v_mov_b32_e32 v18, v28
	v_mov_b32_e32 v19, v28
	v_mov_b32_e32 v12, v28
	v_mov_b32_e32 v13, v28
	v_mov_b32_e32 v14, v28
	v_mov_b32_e32 v15, v28
	v_mov_b32_e32 v20, v28
	v_mov_b32_e32 v21, v28
	v_mov_b32_e32 v22, v28
	v_mov_b32_e32 v4, v28
	v_mov_b32_e32 v5, v28
	v_mov_b32_e32 v6, v28
	v_mov_b32_e32 v7, v28
	v_mov_b32_e32 v0, v28
	v_mov_b32_e32 v1, v28
	v_mov_b32_e32 v2, v28
	v_mov_b32_e32 v3, v28
	v_mov_b32_e32 v8, v28
	v_mov_b32_e32 v9, v28
	v_mov_b32_e32 v10, v28
	v_mov_b32_e32 v11, v28
	s_waitcnt lgkmcnt(0)
	s_barrier
	s_branch .LBB0_156
.LBB0_155:
	s_or_b64 exec, exec, s[0:1]
	s_movk_i32 s0, 0x1040
	v_mad_u64_u32 v[32:33], s[0:1], v33, s0, v[32:33]
	ds_read2_b32 v[38:39], v32 offset1:65
	s_waitcnt lgkmcnt(1)
	v_add_f32_e32 v33, v34, v36
	v_add_f32_e32 v33, v33, v35
	ds_read2_b32 v[34:35], v32 offset0:130 offset1:195
	v_add_f32_e32 v40, v33, v37
	s_waitcnt lgkmcnt(1)
	v_add_f32_e32 v33, v40, v38
	v_add_f32_e32 v38, v40, v39
	v_add_u32_e32 v39, 0x400, v32
	ds_read2_b32 v[36:37], v39 offset0:4 offset1:69
	ds_write2_b32 v32, v33, v38 offset1:65
	s_waitcnt lgkmcnt(2)
	v_add_f32_e32 v33, v40, v34
	v_add_f32_e32 v34, v40, v35
	ds_write2_b32 v32, v33, v34 offset0:130 offset1:195
	ds_read2_b32 v[34:35], v39 offset0:134 offset1:199
	v_add_u32_e32 v41, 0x800, v32
	s_waitcnt lgkmcnt(3)
	v_add_f32_e32 v33, v40, v36
	v_add_f32_e32 v38, v40, v37
	ds_read2_b32 v[36:37], v41 offset0:8 offset1:73
	ds_write2_b32 v39, v33, v38 offset0:4 offset1:69
	s_waitcnt lgkmcnt(2)
	v_add_f32_e32 v33, v40, v34
	v_add_f32_e32 v34, v40, v35
	ds_write2_b32 v39, v33, v34 offset0:134 offset1:199
	ds_read2_b32 v[34:35], v41 offset0:138 offset1:203
	s_waitcnt lgkmcnt(3)
	v_add_f32_e32 v33, v40, v36
	v_add_f32_e32 v36, v40, v37
	ds_write2_b32 v41, v33, v36 offset0:8 offset1:73
	v_add_u32_e32 v36, 0xc00, v32
	ds_read2_b32 v[32:33], v36 offset0:12 offset1:77
	s_waitcnt lgkmcnt(2)
	v_add_f32_e32 v37, v40, v34
	v_add_f32_e32 v38, v40, v35
	ds_read2_b32 v[34:35], v36 offset0:142 offset1:207
	ds_write2_b32 v41, v37, v38 offset0:138 offset1:203
	s_waitcnt lgkmcnt(2)
	v_add_f32_e32 v32, v40, v32
	v_add_f32_e32 v33, v40, v33
	ds_write2_b32 v36, v32, v33 offset0:12 offset1:77
	s_waitcnt lgkmcnt(2)
	v_add_f32_e32 v32, v40, v34
	v_add_f32_e32 v33, v40, v35
	ds_write2_b32 v36, v32, v33 offset0:142 offset1:207
	s_waitcnt lgkmcnt(0)
	s_barrier
	ds_read2_b32 v[32:33], v181 offset1:65
	v_add_u32_e32 v36, 0x400, v181
	v_mov_b32_e32 v63, v129
	v_mov_b32_e32 v65, v129
	v_mov_b32_e32 v67, v129
	s_waitcnt lgkmcnt(0)
	v_mul_f32_e32 v34, 0x3fb8aa3b, v32
	v_exp_f32_e32 v34, v34
	v_mul_f32_e32 v32, 0xbfb8aa3b, v32
	v_exp_f32_e32 v32, v32
	v_mov_b32_e32 v69, v129
	v_mul_f32_e32 v34, v109, v34
	v_cvt_pk_bf16_f32 v34, v34, s0
	ds_write_b16 v182, v34 offset:25856
	v_mul_f32_e32 v34, 0x3fb8aa3b, v33
	v_exp_f32_e32 v34, v34
	v_mul_f32_e32 v32, v32, v110
	v_cvt_pk_bf16_f32 v32, v32, s0
	ds_write_b16 v182, v32 offset:35072
	v_mul_f32_e32 v32, v111, v34
	ds_read2_b32 v[34:35], v181 offset0:130 offset1:195
	v_mul_f32_e32 v33, 0xbfb8aa3b, v33
	v_cvt_pk_bf16_f32 v32, v32, s0
	v_exp_f32_e32 v33, v33
	ds_write_b16 v182, v32 offset:26000
	s_waitcnt lgkmcnt(1)
	v_mul_f32_e32 v32, 0x3fb8aa3b, v34
	v_exp_f32_e32 v32, v32
	v_mul_f32_e32 v33, v33, v112
	v_cvt_pk_bf16_f32 v33, v33, s0
	ds_write_b16 v182, v33 offset:35216
	v_mul_f32_e32 v32, v113, v32
	v_mul_f32_e32 v33, 0xbfb8aa3b, v34
	v_cvt_pk_bf16_f32 v32, v32, s0
	v_exp_f32_e32 v33, v33
	ds_write_b16 v182, v32 offset:26144
	v_mul_f32_e32 v32, 0x3fb8aa3b, v35
	v_exp_f32_e32 v32, v32
	v_mul_f32_e32 v33, v33, v114
	v_cvt_pk_bf16_f32 v33, v33, s0
	ds_write_b16 v182, v33 offset:35360
	v_mul_f32_e32 v34, v115, v32
	ds_read2_b32 v[32:33], v36 offset0:4 offset1:69
	v_cvt_pk_bf16_f32 v34, v34, s0
	ds_write_b16 v182, v34 offset:26288
	v_mul_f32_e32 v35, 0xbfb8aa3b, v35
	v_exp_f32_e32 v35, v35
	s_waitcnt lgkmcnt(1)
	v_mul_f32_e32 v34, 0x3fb8aa3b, v32
	v_exp_f32_e32 v34, v34
	v_mul_f32_e32 v32, 0xbfb8aa3b, v32
	v_exp_f32_e32 v32, v32
	v_mul_f32_e32 v35, v35, v116
	v_mul_f32_e32 v34, v117, v34
	v_cvt_pk_bf16_f32 v34, v34, s0
	ds_write_b16 v182, v34 offset:26432
	v_mul_f32_e32 v34, 0x3fb8aa3b, v33
	v_exp_f32_e32 v34, v34
	v_mul_f32_e32 v32, v32, v118
	v_cvt_pk_bf16_f32 v35, v35, s0
	v_cvt_pk_bf16_f32 v32, v32, s0
	ds_write_b16 v182, v35 offset:35504
	ds_write_b16 v182, v32 offset:35648
	v_mul_f32_e32 v32, v119, v34
	ds_read2_b32 v[34:35], v36 offset0:134 offset1:199
	v_mul_f32_e32 v33, 0xbfb8aa3b, v33
	v_cvt_pk_bf16_f32 v32, v32, s0
	v_exp_f32_e32 v33, v33
	ds_write_b16 v182, v32 offset:26576
	s_waitcnt lgkmcnt(1)
	v_mul_f32_e32 v32, 0x3fb8aa3b, v34
	v_exp_f32_e32 v32, v32
	v_mul_f32_e32 v33, v33, v120
	v_cvt_pk_bf16_f32 v33, v33, s0
	ds_write_b16 v182, v33 offset:35792
	v_mul_f32_e32 v32, v121, v32
	v_mul_f32_e32 v33, 0xbfb8aa3b, v34
	v_cvt_pk_bf16_f32 v32, v32, s0
	v_exp_f32_e32 v33, v33
	ds_write_b16 v182, v32 offset:26720
	v_mul_f32_e32 v32, 0x3fb8aa3b, v35
	v_exp_f32_e32 v32, v32
	v_mul_f32_e32 v33, v33, v122
	v_cvt_pk_bf16_f32 v33, v33, s0
	v_add_u32_e32 v36, 0x800, v181
	ds_write_b16 v182, v33 offset:35936
	v_mul_f32_e32 v34, v123, v32
	ds_read2_b32 v[32:33], v36 offset0:8 offset1:73
	v_cvt_pk_bf16_f32 v34, v34, s0
	ds_write_b16 v182, v34 offset:26864
	v_mul_f32_e32 v35, 0xbfb8aa3b, v35
	v_exp_f32_e32 v35, v35
	s_waitcnt lgkmcnt(1)
	v_mul_f32_e32 v34, 0x3fb8aa3b, v32
	v_exp_f32_e32 v34, v34
	v_mul_f32_e32 v32, 0xbfb8aa3b, v32
	v_exp_f32_e32 v32, v32
	v_mul_f32_e32 v35, v35, v124
	v_mul_f32_e32 v34, v125, v34
	v_cvt_pk_bf16_f32 v34, v34, s0
	ds_write_b16 v182, v34 offset:27008
	v_mul_f32_e32 v34, 0x3fb8aa3b, v33
	v_exp_f32_e32 v34, v34
	v_mul_f32_e32 v32, v32, v126
	v_cvt_pk_bf16_f32 v35, v35, s0
	v_cvt_pk_bf16_f32 v32, v32, s0
	ds_write_b16 v182, v35 offset:36080
	ds_write_b16 v182, v32 offset:36224
	v_mul_f32_e32 v32, v127, v34
	ds_read2_b32 v[34:35], v36 offset0:138 offset1:203
	v_cvt_pk_bf16_f32 v32, v32, s0
	v_mul_f32_e32 v33, 0xbfb8aa3b, v33
	v_exp_f32_e32 v33, v33
	ds_write_b16 v182, v32 offset:27152
	s_waitcnt lgkmcnt(1)
	v_mul_f32_e32 v32, 0x3fb8aa3b, v34
	v_exp_f32_e32 v32, v32
	v_mul_f32_e32 v33, v33, v133
	v_cvt_pk_bf16_f32 v33, v33, s0
	ds_write_b16 v182, v33 offset:36368
	v_mul_f32_e32 v32, v134, v32
	v_cvt_pk_bf16_f32 v32, v32, s0
	v_mul_f32_e32 v33, 0xbfb8aa3b, v34
	v_exp_f32_e32 v33, v33
	ds_write_b16 v182, v32 offset:27296
	v_mul_f32_e32 v32, 0x3fb8aa3b, v35
	v_exp_f32_e32 v32, v32
	v_mul_f32_e32 v33, v33, v135
	v_cvt_pk_bf16_f32 v33, v33, s0
	ds_write_b16 v182, v33 offset:36512
	v_mul_f32_e32 v34, v136, v32
	v_add_u32_e32 v32, 0xc00, v181
	ds_read2_b32 v[32:33], v32 offset0:12 offset1:77
	v_cvt_pk_bf16_f32 v34, v34, s0
	ds_write_b16 v182, v34 offset:27440
	v_mul_f32_e32 v35, 0xbfb8aa3b, v35
	v_exp_f32_e32 v35, v35
	s_waitcnt lgkmcnt(1)
	v_mul_f32_e32 v34, 0x3fb8aa3b, v32
	v_exp_f32_e32 v34, v34
	v_mul_f32_e32 v32, 0xbfb8aa3b, v32
	v_exp_f32_e32 v32, v32
	v_mul_f32_e32 v35, v35, v137
	v_mul_f32_e32 v34, v138, v34
	v_cvt_pk_bf16_f32 v34, v34, s0
	ds_write_b16 v182, v34 offset:27584
	v_mul_f32_e32 v34, 0x3fb8aa3b, v33
	v_exp_f32_e32 v34, v34
	v_mul_f32_e32 v32, v32, v139
	v_mul_f32_e32 v33, 0xbfb8aa3b, v33
	v_cvt_pk_bf16_f32 v32, v32, s0
	v_exp_f32_e32 v33, v33
	ds_write_b16 v182, v32 offset:36800
	v_mul_f32_e32 v32, v140, v34
	ds_read_b32 v34, v181 offset:3640
	v_cvt_pk_bf16_f32 v32, v32, s0
	ds_write_b16 v182, v32 offset:27728
	v_mul_f32_e32 v32, v33, v141
	v_cvt_pk_bf16_f32 v35, v35, s0
	v_cvt_pk_bf16_f32 v32, v32, s0
	ds_write_b16 v182, v35 offset:36656
	ds_read_b32 v33, v183
	s_waitcnt lgkmcnt(3)
	v_mul_f32_e32 v35, 0x3fb8aa3b, v34
	ds_write_b16 v182, v32 offset:36944
	v_mul_f32_e32 v32, 0xbfb8aa3b, v34
	v_exp_f32_e32 v35, v35
	v_exp_f32_e32 v32, v32
	v_mov_b32_e32 v71, v129
	v_mov_b32_e32 v73, v129
	v_mul_f32_e32 v34, v142, v35
	v_mul_f32_e32 v32, v32, v143
	v_cvt_pk_bf16_f32 v34, v34, s0
	v_cvt_pk_bf16_f32 v32, v32, s0
	ds_write_b16 v182, v34 offset:27872
	s_waitcnt lgkmcnt(2)
	v_mul_f32_e32 v34, 0x3fb8aa3b, v33
	ds_write_b16 v182, v32 offset:37088
	v_mul_f32_e32 v32, 0xbfb8aa3b, v33
	v_exp_f32_e32 v34, v34
	v_exp_f32_e32 v32, v32
	v_mov_b32_e32 v75, v129
	v_mul_f32_e32 v33, v144, v34
	v_mul_f32_e32 v32, v32, v145
	v_cvt_pk_bf16_f32 v33, v33, s0
	v_cvt_pk_bf16_f32 v32, v32, s0
	ds_write_b16 v184, v33 offset:25856
	ds_write_b16 v184, v32 offset:35072
	s_waitcnt lgkmcnt(0)
	s_barrier
	ds_read_b128 v[36:39], v185 offset:25856
	ds_read_b128 v[40:43], v186 offset:35072
	ds_read_b128 v[32:35], v185 offset:25920
	ds_read_b128 v[44:47], v186 offset:35136
	s_waitcnt lgkmcnt(2)
	v_mfma_f32_16x16x32_bf16 v[40:43], v[36:39], v[40:43], 0
	s_waitcnt lgkmcnt(0)
	v_mfma_f32_16x16x32_bf16 v[40:43], v[32:35], v[44:47], v[40:43]
	v_cndmask_b32_e64 v44, 0, 1, s[38:39]
	v_cndmask_b32_e64 v45, 0, 1, s[36:37]
	v_cndmask_b32_e64 v44, v45, v44, s[30:31]
	v_and_b32_e32 v44, 1, v44
	v_cmp_eq_u32_e32 vcc, 1, v44
	s_nop 2
	v_cvt_pk_bf16_f32 v40, v40, s0
	v_add_u32_e32 v44, v58, v180
	v_cndmask_b32_e32 v40, 0, v40, vcc
	ds_write_b16 v44, v40
	v_cndmask_b32_e64 v40, 0, 1, s[42:43]
	v_cndmask_b32_e64 v45, 0, 1, s[40:41]
	v_cndmask_b32_e64 v40, v45, v40, s[30:31]
	v_and_b32_e32 v40, 1, v40
	v_cvt_pk_bf16_f32 v41, v41, s0
	v_cmp_eq_u32_e32 vcc, 1, v40
	s_nop 1
	v_cndmask_b32_e32 v40, 0, v41, vcc
	ds_write_b16 v44, v40 offset:144
	v_cndmask_b32_e64 v40, 0, 1, s[46:47]
	v_cndmask_b32_e64 v41, 0, 1, s[44:45]
	v_cndmask_b32_e64 v40, v41, v40, s[30:31]
	v_and_b32_e32 v40, 1, v40
	v_cvt_pk_bf16_f32 v41, v42, s0
	v_cmp_eq_u32_e32 vcc, 1, v40
	s_nop 1
	v_cndmask_b32_e32 v40, 0, v41, vcc
	ds_write_b16 v44, v40 offset:288
	v_cndmask_b32_e64 v40, 0, 1, s[50:51]
	v_cndmask_b32_e64 v41, 0, 1, s[48:49]
	v_cndmask_b32_e64 v40, v41, v40, s[30:31]
	v_and_b32_e32 v40, 1, v40
	v_cvt_pk_bf16_f32 v41, v43, s0
	v_cmp_eq_u32_e32 vcc, 1, v40
	s_nop 1
	v_cndmask_b32_e32 v40, 0, v41, vcc
	ds_write_b16 v44, v40 offset:432
	ds_read_b128 v[40:43], v186 offset:37376
	ds_read_b128 v[44:47], v186 offset:37440
	s_waitcnt lgkmcnt(1)
	v_mfma_f32_16x16x32_bf16 v[40:43], v[36:39], v[40:43], 0
	s_waitcnt lgkmcnt(0)
	v_mfma_f32_16x16x32_bf16 v[40:43], v[32:35], v[44:47], v[40:43]
	v_cndmask_b32_e64 v44, 0, 1, s[54:55]
	v_cndmask_b32_e64 v45, 0, 1, s[52:53]
	v_cndmask_b32_e64 v44, v45, v44, s[30:31]
	v_and_b32_e32 v44, 1, v44
	v_cmp_eq_u32_e32 vcc, 1, v44
	s_nop 2
	v_cvt_pk_bf16_f32 v40, v40, s0
	v_cndmask_b32_e64 v44, 0, 1, s[56:57]
	v_cndmask_b32_e32 v40, 0, v40, vcc
	ds_write_b16 v187, v40
	v_cndmask_b32_e64 v40, 0, 1, s[58:59]
	v_cndmask_b32_e64 v40, v44, v40, s[30:31]
	v_and_b32_e32 v40, 1, v40
	v_cvt_pk_bf16_f32 v41, v41, s0
	v_cmp_eq_u32_e32 vcc, 1, v40
	s_nop 1
	v_cndmask_b32_e32 v40, 0, v41, vcc
	ds_write_b16 v187, v40 offset:144
	v_cndmask_b32_e64 v40, 0, 1, s[62:63]
	v_cndmask_b32_e64 v41, 0, 1, s[60:61]
	v_cndmask_b32_e64 v40, v41, v40, s[30:31]
	v_and_b32_e32 v40, 1, v40
	v_cvt_pk_bf16_f32 v41, v42, s0
	v_cmp_eq_u32_e32 vcc, 1, v40
	s_nop 1
	v_cndmask_b32_e32 v40, 0, v41, vcc
	ds_write_b16 v187, v40 offset:288
	v_cndmask_b32_e64 v40, 0, 1, s[66:67]
	v_cndmask_b32_e64 v41, 0, 1, s[64:65]
	v_cndmask_b32_e64 v40, v41, v40, s[30:31]
	v_and_b32_e32 v40, 1, v40
	v_cvt_pk_bf16_f32 v41, v43, s0
	v_cmp_eq_u32_e32 vcc, 1, v40
	s_nop 1
	v_cndmask_b32_e32 v40, 0, v41, vcc
	ds_write_b16 v187, v40 offset:432
	ds_read_b128 v[40:43], v186 offset:39680
	ds_read_b128 v[44:47], v186 offset:39744
	s_waitcnt lgkmcnt(1)
	v_mfma_f32_16x16x32_bf16 v[40:43], v[36:39], v[40:43], 0
	s_waitcnt lgkmcnt(0)
	v_mfma_f32_16x16x32_bf16 v[40:43], v[32:35], v[44:47], v[40:43]
	v_cndmask_b32_e64 v44, 0, 1, s[70:71]
	v_cndmask_b32_e64 v45, 0, 1, s[68:69]
	v_cndmask_b32_e64 v44, v45, v44, s[30:31]
	v_and_b32_e32 v44, 1, v44
	v_cmp_eq_u32_e32 vcc, 1, v44
	s_nop 2
	v_cvt_pk_bf16_f32 v40, v40, s0
	v_cndmask_b32_e64 v44, 0, 1, s[72:73]
	v_cndmask_b32_e32 v40, 0, v40, vcc
	ds_write_b16 v188, v40
	v_cndmask_b32_e64 v40, 0, 1, s[74:75]
	v_cndmask_b32_e64 v40, v44, v40, s[30:31]
	v_and_b32_e32 v40, 1, v40
	v_cvt_pk_bf16_f32 v41, v41, s0
	v_cmp_eq_u32_e32 vcc, 1, v40
	s_nop 1
	v_cndmask_b32_e32 v40, 0, v41, vcc
	ds_write_b16 v188, v40 offset:144
	v_cndmask_b32_e64 v40, 0, 1, s[78:79]
	v_cndmask_b32_e64 v41, 0, 1, s[76:77]
	v_cndmask_b32_e64 v40, v41, v40, s[30:31]
	v_and_b32_e32 v40, 1, v40
	v_cvt_pk_bf16_f32 v41, v42, s0
	v_cmp_eq_u32_e32 vcc, 1, v40
	s_nop 1
	v_cndmask_b32_e32 v40, 0, v41, vcc
	ds_write_b16 v188, v40 offset:288
	v_cndmask_b32_e64 v40, 0, 1, s[82:83]
	v_cndmask_b32_e64 v41, 0, 1, s[80:81]
	v_cndmask_b32_e64 v40, v41, v40, s[30:31]
	v_and_b32_e32 v40, 1, v40
	v_cvt_pk_bf16_f32 v41, v43, s0
	v_cmp_eq_u32_e32 vcc, 1, v40
	s_nop 1
	v_cndmask_b32_e32 v40, 0, v41, vcc
	ds_write_b16 v188, v40 offset:432
	ds_read_b128 v[40:43], v186 offset:41984
	ds_read_b128 v[44:47], v186 offset:42048
	s_waitcnt lgkmcnt(1)
	v_mfma_f32_16x16x32_bf16 v[40:43], v[36:39], v[40:43], 0
	s_waitcnt lgkmcnt(0)
	v_mfma_f32_16x16x32_bf16 v[40:43], v[32:35], v[44:47], v[40:43]
	v_cndmask_b32_e64 v44, 0, 1, s[86:87]
	v_cndmask_b32_e64 v45, 0, 1, s[84:85]
	v_cndmask_b32_e64 v44, v45, v44, s[30:31]
	v_and_b32_e32 v44, 1, v44
	v_cmp_eq_u32_e32 vcc, 1, v44
	s_nop 2
	v_cvt_pk_bf16_f32 v40, v40, s0
	v_cndmask_b32_e64 v44, 0, 1, s[88:89]
	v_cndmask_b32_e32 v40, 0, v40, vcc
	ds_write_b16 v189, v40
	v_cndmask_b32_e64 v40, 0, 1, s[90:91]
	v_cndmask_b32_e64 v40, v44, v40, s[30:31]
	v_and_b32_e32 v40, 1, v40
	v_cvt_pk_bf16_f32 v41, v41, s0
	v_cmp_eq_u32_e32 vcc, 1, v40
	s_nop 1
	v_cndmask_b32_e32 v40, 0, v41, vcc
	ds_write_b16 v189, v40 offset:144
	v_cndmask_b32_e64 v40, 0, 1, s[94:95]
	v_cndmask_b32_e64 v41, 0, 1, s[92:93]
	v_cndmask_b32_e64 v40, v41, v40, s[30:31]
	v_and_b32_e32 v40, 1, v40
	v_cvt_pk_bf16_f32 v41, v42, s0
	v_cmp_eq_u32_e32 vcc, 1, v40
	s_nop 1
	v_cndmask_b32_e32 v40, 0, v41, vcc
	ds_write_b16 v189, v40 offset:288
	v_cndmask_b32_e64 v40, 0, 1, s[98:99]
	v_cndmask_b32_e64 v41, 0, 1, s[96:97]
	v_cndmask_b32_e64 v40, v41, v40, s[30:31]
	v_cvt_pk_bf16_f32 v41, v43, s0
	s_or_b32 s0, s25, s24
	s_ashr_i32 s1, s0, 31
	v_and_b32_e32 v40, 1, v40
	s_lshl_b64 s[0:1], s[0:1], 14
	v_cmp_eq_u32_e32 vcc, 1, v40
	v_lshl_add_u64 v[76:77], v[60:61], 0, s[0:1]
	v_lshl_add_u64 v[196:197], v[76:77], 0, v[128:129]
	v_cndmask_b32_e32 v40, 0, v41, vcc
	ds_write_b16 v189, v40 offset:432
	s_waitcnt lgkmcnt(0)
	s_barrier
	s_xor_b64 s[0:1], s[30:31], -1
	s_mov_b32 s25, 1
	s_andn2_b64 vcc, exec, s[0:1]
	s_mov_b64 s[30:31], 0
	v_lshl_add_u64 v[248:249], v[76:77], 0, v[128:129]
	global_load_dwordx4 v[232:235], v[248:249], off
	v_lshl_add_u64 v[248:249], v[76:77], 0, v[128:129]
	global_load_dwordx4 v[236:239], v[248:249], off offset:64
	v_lshl_add_u64 v[248:249], v[76:77], 0, v[62:63]
	global_load_dwordx4 v[240:243], v[248:249], off
	v_lshl_add_u64 v[248:249], v[76:77], 0, v[62:63]
	global_load_dwordx4 v[244:247], v[248:249], off offset:64
	v_lshl_add_u64 v[248:249], v[76:77], 0, v[64:65]
	global_load_dwordx4 v[216:219], v[248:249], off
	v_lshl_add_u64 v[248:249], v[76:77], 0, v[64:65]
	global_load_dwordx4 v[80:83], v[248:249], off offset:64
	ds_read_b128 v[40:43], v185
	ds_read_b128 v[44:47], v185 offset:64
	ds_read_b64_tr_b16 v[192:193], v190 offset:44288
	ds_read_b64_tr_b16 v[194:195], v190 offset:45376
	ds_read_b64_tr_b16 v[196:197], v190 offset:52992
	ds_read_b64_tr_b16 v[198:199], v190 offset:54080
	s_waitcnt lgkmcnt(0)
	v_mfma_f32_16x16x32_bf16 v[28:31], v[40:43], v[192:195], v[28:31]
	s_waitcnt vmcnt(5)
	v_mfma_f32_16x16x32_bf16 v[28:31], v[36:39], v[232:235], v[28:31]
	v_lshl_add_u64 v[248:249], v[76:77], 0, v[66:67]
	global_load_dwordx4 v[232:235], v[248:249], off
	v_mfma_f32_16x16x32_bf16 v[28:31], v[44:47], v[196:199], v[28:31]
	s_waitcnt vmcnt(5)
	v_mfma_f32_16x16x32_bf16 v[28:31], v[32:35], v[236:239], v[28:31]
	v_lshl_add_u64 v[248:249], v[76:77], 0, v[66:67]
	global_load_dwordx4 v[236:239], v[248:249], off offset:64
	ds_read_b64_tr_b16 v[192:193], v190 offset:44320
	ds_read_b64_tr_b16 v[194:195], v190 offset:45408
	ds_read_b64_tr_b16 v[196:197], v190 offset:53024
	ds_read_b64_tr_b16 v[198:199], v190 offset:54112
	s_waitcnt lgkmcnt(0)
	v_mfma_f32_16x16x32_bf16 v[16:19], v[40:43], v[192:195], v[16:19]
	s_waitcnt vmcnt(5)
	v_mfma_f32_16x16x32_bf16 v[16:19], v[36:39], v[240:243], v[16:19]
	v_lshl_add_u64 v[248:249], v[76:77], 0, v[68:69]
	global_load_dwordx4 v[240:243], v[248:249], off
	v_mfma_f32_16x16x32_bf16 v[16:19], v[44:47], v[196:199], v[16:19]
	s_waitcnt vmcnt(5)
	v_mfma_f32_16x16x32_bf16 v[16:19], v[32:35], v[244:247], v[16:19]
	v_lshl_add_u64 v[248:249], v[76:77], 0, v[68:69]
	global_load_dwordx4 v[244:247], v[248:249], off offset:64
	ds_read_b64_tr_b16 v[192:193], v190 offset:44352
	ds_read_b64_tr_b16 v[194:195], v190 offset:45440
	ds_read_b64_tr_b16 v[196:197], v190 offset:53056
	ds_read_b64_tr_b16 v[198:199], v190 offset:54144
	s_waitcnt lgkmcnt(0)
	v_mfma_f32_16x16x32_bf16 v[12:15], v[40:43], v[192:195], v[12:15]
	s_waitcnt vmcnt(5)
	v_mfma_f32_16x16x32_bf16 v[12:15], v[36:39], v[216:219], v[12:15]
	v_lshl_add_u64 v[248:249], v[76:77], 0, v[70:71]
	global_load_dwordx4 v[216:219], v[248:249], off
	v_mfma_f32_16x16x32_bf16 v[12:15], v[44:47], v[196:199], v[12:15]
	s_waitcnt vmcnt(5)
	v_mfma_f32_16x16x32_bf16 v[12:15], v[32:35], v[80:83], v[12:15]
	v_lshl_add_u64 v[248:249], v[76:77], 0, v[70:71]
	global_load_dwordx4 v[80:83], v[248:249], off offset:64
	ds_read_b64_tr_b16 v[192:193], v190 offset:44384
	ds_read_b64_tr_b16 v[194:195], v190 offset:45472
	ds_read_b64_tr_b16 v[196:197], v190 offset:53088
	ds_read_b64_tr_b16 v[198:199], v190 offset:54176
	s_waitcnt lgkmcnt(0)
	v_mfma_f32_16x16x32_bf16 v[24:27], v[40:43], v[192:195], v[24:27]
	s_waitcnt vmcnt(5)
	v_mfma_f32_16x16x32_bf16 v[24:27], v[36:39], v[232:235], v[24:27]
	v_lshl_add_u64 v[248:249], v[76:77], 0, v[72:73]
	global_load_dwordx4 v[232:235], v[248:249], off
	v_mfma_f32_16x16x32_bf16 v[24:27], v[44:47], v[196:199], v[24:27]
	s_waitcnt vmcnt(5)
	v_mfma_f32_16x16x32_bf16 v[24:27], v[32:35], v[236:239], v[24:27]
	v_lshl_add_u64 v[248:249], v[76:77], 0, v[72:73]
	global_load_dwordx4 v[236:239], v[248:249], off offset:64
	ds_read_b64_tr_b16 v[192:193], v190 offset:44416
	ds_read_b64_tr_b16 v[194:195], v190 offset:45504
	ds_read_b64_tr_b16 v[196:197], v190 offset:53120
	ds_read_b64_tr_b16 v[198:199], v190 offset:54208
	s_waitcnt lgkmcnt(0)
	v_mfma_f32_16x16x32_bf16 v[20:23], v[40:43], v[192:195], v[20:23]
	s_waitcnt vmcnt(5)
	v_mfma_f32_16x16x32_bf16 v[20:23], v[36:39], v[240:243], v[20:23]
	v_lshl_add_u64 v[248:249], v[76:77], 0, v[74:75]
	global_load_dwordx4 v[240:243], v[248:249], off
	v_mfma_f32_16x16x32_bf16 v[20:23], v[44:47], v[196:199], v[20:23]
	s_waitcnt vmcnt(5)
	v_mfma_f32_16x16x32_bf16 v[20:23], v[32:35], v[244:247], v[20:23]
	v_lshl_add_u64 v[248:249], v[76:77], 0, v[74:75]
	global_load_dwordx4 v[244:247], v[248:249], off offset:64
	ds_read_b64_tr_b16 v[192:193], v190 offset:44448
	ds_read_b64_tr_b16 v[194:195], v190 offset:45536
	ds_read_b64_tr_b16 v[196:197], v190 offset:53152
	ds_read_b64_tr_b16 v[198:199], v190 offset:54240
	s_waitcnt lgkmcnt(0)
	v_mfma_f32_16x16x32_bf16 v[4:7], v[40:43], v[192:195], v[4:7]
	s_waitcnt vmcnt(5)
	v_mfma_f32_16x16x32_bf16 v[4:7], v[36:39], v[216:219], v[4:7]
	v_mfma_f32_16x16x32_bf16 v[4:7], v[44:47], v[196:199], v[4:7]
	s_waitcnt vmcnt(4)
	v_mfma_f32_16x16x32_bf16 v[4:7], v[32:35], v[80:83], v[4:7]
	ds_read_b64_tr_b16 v[192:193], v190 offset:44480
	ds_read_b64_tr_b16 v[194:195], v190 offset:45568
	ds_read_b64_tr_b16 v[196:197], v190 offset:53184
	ds_read_b64_tr_b16 v[198:199], v190 offset:54272
	s_waitcnt lgkmcnt(0)
	v_mfma_f32_16x16x32_bf16 v[0:3], v[40:43], v[192:195], v[0:3]
	s_waitcnt vmcnt(3)
	v_mfma_f32_16x16x32_bf16 v[0:3], v[36:39], v[232:235], v[0:3]
	v_mfma_f32_16x16x32_bf16 v[0:3], v[44:47], v[196:199], v[0:3]
	s_waitcnt vmcnt(2)
	v_mfma_f32_16x16x32_bf16 v[0:3], v[32:35], v[236:239], v[0:3]
	ds_read_b64_tr_b16 v[192:193], v190 offset:44512
	ds_read_b64_tr_b16 v[194:195], v190 offset:45600
	ds_read_b64_tr_b16 v[196:197], v190 offset:53216
	ds_read_b64_tr_b16 v[198:199], v190 offset:54304
	s_waitcnt lgkmcnt(0)
	s_barrier
	v_mfma_f32_16x16x32_bf16 v[8:11], v[40:43], v[192:195], v[8:11]
	s_waitcnt vmcnt(1)
	v_mfma_f32_16x16x32_bf16 v[8:11], v[36:39], v[240:243], v[8:11]
	v_mfma_f32_16x16x32_bf16 v[8:11], v[44:47], v[196:199], v[8:11]
	s_waitcnt vmcnt(0)
	v_mfma_f32_16x16x32_bf16 v[8:11], v[32:35], v[244:247], v[8:11]
	s_cbranch_vccz .LBB0_134
